# up GEMM: first K-iteration after each epilogue peeled with relaxed vmcnt(16) waits, As[1][1] stage hoisted before the epilogue, so epilogue stores drain under the next tile's first two K-tiles
# speedup vs baseline: 1.5474x; 1.5474x over previous
; #define PG8_STAGE(bufoff, gbase, voff) do { _Pragma("unroll") for (int _i = 0; _i < 2; ++_i) \
;         __builtin_amdgcn_global_load_lds((const unsigned*)((const char*)(gbase) + (voff)[_i]), (PG8_LAS unsigned*)(lds + (bufoff) + ldsw + _i * 8192), 16, 0, 0); } while (0)
; #define PG8_LDA(dst, b, h) do { _Pragma("unroll") for (int m = 0; m < 4; ++m) _Pragma("unroll") for (int k = 0; k < 2; ++k) dst[m][k] = *(const PG8_LAS bf16x8*)(lds + PG8_SA(b, h) + aoff + m * 2048 + k * 1024); } while (0)
; #define PG8_LDB(dst, b, h) do { _Pragma("unroll") for (int n = 0; n < 2; ++n) _Pragma("unroll") for (int k = 0; k < 2; ++k) dst[n][k] = *(const PG8_LAS bf16x8*)(lds + PG8_SB(b, h) + boff + n * 2048 + k * 1024); } while (0)
; #define PG8_SCHED __builtin_amdgcn_sched_barrier(0)
; template <class Epi, class Sched, bool ALIGN_EPI = false, bool SP2 = false>
; __device__ __forceinline__ void gemm_phase(PG8_LAS unsigned char* lds, const Gemm g, const Sched& S, const Epi& E) {
;     ...
;         const bool has_next = S.next(ui + 1, nxt);
;         const char* nA = has_next ? (const char*)g.A + (size_t)nxt.pm * tstep : cA; const char* nB = has_next ? (const char*)g.Bt + (size_t)nxt.pn * tstep : cB;
;         for (int t = 0; t < nt; t += 2) {
;             const bool last = (t == nt - 2);
;             const char* a1 = cA + (size_t)(t + 1) * kstep;
;             const char* a2 = last ? nA : cA + (size_t)(t + 2) * kstep; const char* b2 = last ? nB : cB + (size_t)(t + 2) * kstep;
;             const char* a3 = a2 + kstep; const char* b3 = b2 + kstep;
;             if (last && has_next) S.a_ready(nxt);
;             if constexpr (SP2) {
;             PG8_LDB(B0, 0, 0); PG8_LDB(B1, 0, 1); PG8_SCHED; PG8_LDA(At, 0, 0); PG8_STAGE(PG8_SA(1, 1), a1 + hstep, voffA);
;     ...
; #pragma unroll
;         for (int a = 0; a < 2; ++a)
; #pragma unroll
;             for (int b = 0; b < 2; ++b)
; #pragma unroll
;                 for (int m = 0; m < 4; ++m)
; #pragma unroll
;                     for (int n = 0; n < 2; ++n) acc[a][b][m][n] = (f32x4){0.f, 0.f, 0.f, 0.f};
.LBB0_445:
	s_ashr_i32 s7, s6, 31
	s_lshl_b64 s[10:11], s[6:7], 19
	s_add_u32 s10, s23, s10
	s_addc_u32 s11, s24, s11
	s_and_b64 s[12:13], s[8:9], exec
	s_cselect_b32 s7, s11, s15
	s_cselect_b32 s49, s10, s14
	s_ashr_i32 s5, s4, 31
	s_lshl_b64 s[12:13], s[4:5], 19
	s_add_u32 s12, s25, s12
	s_addc_u32 s13, s26, s13
	s_and_b64 s[18:19], s[8:9], exec
	s_cselect_b32 s5, s13, s17
	s_cselect_b32 s50, s12, s16
	s_add_u32 s14, s14, 0x40080
	s_addc_u32 s15, s15, 0
	s_add_u32 s51, s16, 0x100
	v_mov_b32_e32 v0, 0
	s_addc_u32 s52, s17, 0
	s_mov_b32 s53, -2
	v_mov_b32_e32 v1, v0
	v_mov_b32_e32 v2, v0
	v_mov_b32_e32 v3, v0
	v_mov_b32_e32 v8, v0
	v_mov_b32_e32 v9, v0
	v_mov_b32_e32 v10, v0
	v_mov_b32_e32 v11, v0
	v_mov_b32_e32 v16, v0
	v_mov_b32_e32 v17, v0
	v_mov_b32_e32 v18, v0
	v_mov_b32_e32 v19, v0
	v_mov_b32_e32 v24, v0
	v_mov_b32_e32 v25, v0
	v_mov_b32_e32 v26, v0
	v_mov_b32_e32 v27, v0
	v_mov_b32_e32 v32, v0
	v_mov_b32_e32 v33, v0
	v_mov_b32_e32 v34, v0
	v_mov_b32_e32 v35, v0
	v_mov_b32_e32 v40, v0
	v_mov_b32_e32 v41, v0
	v_mov_b32_e32 v42, v0
	v_mov_b32_e32 v43, v0
	v_mov_b32_e32 v48, v0
	v_mov_b32_e32 v49, v0
	v_mov_b32_e32 v50, v0
	v_mov_b32_e32 v51, v0
	v_mov_b32_e32 v56, v0
	v_mov_b32_e32 v57, v0
	v_mov_b32_e32 v58, v0
	v_mov_b32_e32 v59, v0
	v_mov_b32_e32 v4, v0
	v_mov_b32_e32 v5, v0
	v_mov_b32_e32 v6, v0
	v_mov_b32_e32 v7, v0
	v_mov_b32_e32 v12, v0
	v_mov_b32_e32 v13, v0
	v_mov_b32_e32 v14, v0
	v_mov_b32_e32 v15, v0
	v_mov_b32_e32 v20, v0
	v_mov_b32_e32 v21, v0
	v_mov_b32_e32 v22, v0
	v_mov_b32_e32 v23, v0
	v_mov_b32_e32 v28, v0
	v_mov_b32_e32 v29, v0
	v_mov_b32_e32 v30, v0
	v_mov_b32_e32 v31, v0
	v_mov_b32_e32 v36, v0
	v_mov_b32_e32 v37, v0
	v_mov_b32_e32 v38, v0
	v_mov_b32_e32 v39, v0
	v_mov_b32_e32 v44, v0
	v_mov_b32_e32 v45, v0
	v_mov_b32_e32 v46, v0
	v_mov_b32_e32 v47, v0
	v_mov_b32_e32 v52, v0
	v_mov_b32_e32 v53, v0
	v_mov_b32_e32 v54, v0
	v_mov_b32_e32 v55, v0
	v_mov_b32_e32 v60, v0
	v_mov_b32_e32 v61, v0
	v_mov_b32_e32 v62, v0
	v_mov_b32_e32 v63, v0
	v_mov_b32_e32 v64, v0
	v_mov_b32_e32 v65, v0
	v_mov_b32_e32 v66, v0
	v_mov_b32_e32 v67, v0
	v_mov_b32_e32 v72, v0
	v_mov_b32_e32 v73, v0
	v_mov_b32_e32 v74, v0
	v_mov_b32_e32 v75, v0
	v_mov_b32_e32 v80, v0
	v_mov_b32_e32 v81, v0
	v_mov_b32_e32 v82, v0
	v_mov_b32_e32 v83, v0
	v_mov_b32_e32 v88, v0
	v_mov_b32_e32 v89, v0
	v_mov_b32_e32 v90, v0
	v_mov_b32_e32 v91, v0
	v_mov_b32_e32 v96, v0
	v_mov_b32_e32 v97, v0
	v_mov_b32_e32 v98, v0
	v_mov_b32_e32 v99, v0
	v_mov_b32_e32 v104, v0
	v_mov_b32_e32 v105, v0
	v_mov_b32_e32 v106, v0
	v_mov_b32_e32 v107, v0
	v_mov_b32_e32 v112, v0
	v_mov_b32_e32 v113, v0
	v_mov_b32_e32 v114, v0
	v_mov_b32_e32 v115, v0
	v_mov_b32_e32 v120, v0
	v_mov_b32_e32 v121, v0
	v_mov_b32_e32 v122, v0
	v_mov_b32_e32 v123, v0
	v_mov_b32_e32 v68, v0
	v_mov_b32_e32 v69, v0
	v_mov_b32_e32 v70, v0
	v_mov_b32_e32 v71, v0
	v_mov_b32_e32 v76, v0
	v_mov_b32_e32 v77, v0
	v_mov_b32_e32 v78, v0
	v_mov_b32_e32 v79, v0
	v_mov_b32_e32 v84, v0
	v_mov_b32_e32 v85, v0
	v_mov_b32_e32 v86, v0
	v_mov_b32_e32 v87, v0
	v_mov_b32_e32 v92, v0
	v_mov_b32_e32 v93, v0
	v_mov_b32_e32 v94, v0
	v_mov_b32_e32 v95, v0
	v_mov_b32_e32 v100, v0
	v_mov_b32_e32 v101, v0
	v_mov_b32_e32 v102, v0
	v_mov_b32_e32 v103, v0
	v_mov_b32_e32 v108, v0
	v_mov_b32_e32 v109, v0
	v_mov_b32_e32 v110, v0
	v_mov_b32_e32 v111, v0
	v_mov_b32_e32 v116, v0
	v_mov_b32_e32 v117, v0
	v_mov_b32_e32 v118, v0
	v_mov_b32_e32 v119, v0
	v_mov_b32_e32 v124, v0
	v_mov_b32_e32 v125, v0
	v_mov_b32_e32 v126, v0
	v_mov_b32_e32 v127, v0
	s_cmp_eq_u32 s48, 0
	s_cbranch_scc1 .LBB0_446
.Lup_peel:
	v_or_b32_e32 v140, 0x10000, v166
	v_add_u32_e32 v162, 0x10400, v166
	ds_read_b128 v[140:143], v140
	ds_read_b128 v[168:171], v162
	v_add_u32_e32 v162, 0x10800, v166
	v_add_u32_e32 v163, 0x10c00, v166
	ds_read_b128 v[172:175], v162
	ds_read_b128 v[176:179], v163
	v_or_b32_e32 v162, 0x14000, v166
	v_add_u32_e32 v163, 0x14400, v166
	ds_read_b128 v[180:183], v162
	ds_read_b128 v[184:187], v163
	v_add_u32_e32 v162, 0x14800, v166
	v_add_u32_e32 v163, 0x14c00, v166
	ds_read_b128 v[188:191], v162
	ds_read_b128 v[210:213], v163
	s_add_u32 s16, s14, 0xfffc0080
	s_addc_u32 s17, s15, -1
	s_cmp_eq_u32 s53, 12
	s_cselect_b32 s19, s7, s17
	s_cselect_b32 s18, s49, s16
	s_cselect_b32 s17, s5, s52
	s_cselect_b32 s16, s50, s51
	ds_read_b128 v[214:217], v165
	ds_read_b128 v[218:221], v165 offset:1024
	ds_read_b128 v[222:225], v165 offset:2048
	ds_read_b128 v[226:229], v165 offset:3072
	ds_read_b128 v[230:233], v165 offset:4096
	ds_read_b128 v[234:237], v165 offset:5120
	ds_read_b128 v[238:241], v165 offset:6144
	ds_read_b128 v[242:245], v165 offset:7168
	s_waitcnt vmcnt(16)
	s_waitcnt lgkmcnt(0)
	s_barrier
; #define PG8_STAGE(bufoff, gbase, voff) do { _Pragma("unroll") for (int _i = 0; _i < 2; ++_i) \
;         __builtin_amdgcn_global_load_lds((const unsigned*)((const char*)(gbase) + (voff)[_i]), (PG8_LAS unsigned*)(lds + (bufoff) + ldsw + _i * 8192), 16, 0, 0); } while (0)
; #define PG8_LDA(dst, b, h) do { _Pragma("unroll") for (int m = 0; m < 4; ++m) _Pragma("unroll") for (int k = 0; k < 2; ++k) dst[m][k] = *(const PG8_LAS bf16x8*)(lds + PG8_SA(b, h) + aoff + m * 2048 + k * 1024); } while (0)
; #define PG8_MMA(ai, bj, At, Bt) do { __builtin_amdgcn_s_setprio(1); _Pragma("unroll") for (int m = 0; m < 4; ++m) _Pragma("unroll") for (int n = 0; n < 2; ++n) _Pragma("unroll") for (int k = 0; k < 2; ++k) \
;         acc[ai][bj][m][n] = __builtin_amdgcn_mfma_f32_16x16x32_bf16(Bt[n][k], At[m][k], acc[ai][bj][m][n], 0, 0, 0); __builtin_amdgcn_s_setprio(0); } while (0)
; #define PG8_WAIT_V(n) asm volatile("s_waitcnt vmcnt(" #n ")" ::: "memory")
; #define PG8_WAIT_L(n) asm volatile("s_waitcnt lgkmcnt(" #n ")" ::: "memory")
; #define PG8_BAR __builtin_amdgcn_s_barrier()
; #define PG8_SCHED __builtin_amdgcn_sched_barrier(0)
; template <class Epi, class Sched, bool ALIGN_EPI = false, bool SP2 = false>
; __device__ __forceinline__ void gemm_phase(PG8_LAS unsigned char* lds, const Gemm g, const Sched& S, const Epi& E) {
;     ...
;             PG8_WAIT_V(8); PG8_WAIT_L(0); PG8_BAR; PG8_MMA(0, 0, At, B0); PG8_MMA(0, 1, At, B1); PG8_BAR; PG8_SCHED;
;             PG8_LDA(At, 0, 1); PG8_STAGE(PG8_SB(0, 0), b2, voffB); PG8_STAGE(PG8_SB(0, 1), b2 + hstep, voffB); PG8_STAGE(PG8_SA(0, 0), a2, voffA);
;             PG8_WAIT_V(8); PG8_WAIT_L(0); PG8_BAR; PG8_MMA(1, 0, At, B0); PG8_MMA(1, 1, At, B1); PG8_BAR; PG8_SCHED;
	s_setprio 1
	s_waitcnt lgkmcnt(0)
	v_mfma_f32_16x16x32_bf16 v[124:127], v[140:143], v[214:217], v[124:127]
	v_mfma_f32_16x16x32_bf16 v[116:119], v[172:175], v[214:217], v[116:119]
	v_mfma_f32_16x16x32_bf16 v[108:111], v[140:143], v[222:225], v[108:111]
	v_mfma_f32_16x16x32_bf16 v[100:103], v[172:175], v[222:225], v[100:103]
	v_mfma_f32_16x16x32_bf16 v[92:95], v[140:143], v[230:233], v[92:95]
	v_mfma_f32_16x16x32_bf16 v[84:87], v[172:175], v[230:233], v[84:87]
	v_mfma_f32_16x16x32_bf16 v[76:79], v[140:143], v[238:241], v[76:79]
	v_mfma_f32_16x16x32_bf16 v[68:71], v[172:175], v[238:241], v[68:71]
	v_mfma_f32_16x16x32_bf16 v[124:127], v[168:171], v[218:221], v[124:127]
	v_mfma_f32_16x16x32_bf16 v[116:119], v[176:179], v[218:221], v[116:119]
	v_mfma_f32_16x16x32_bf16 v[108:111], v[168:171], v[226:229], v[108:111]
	v_mfma_f32_16x16x32_bf16 v[100:103], v[176:179], v[226:229], v[100:103]
	v_mfma_f32_16x16x32_bf16 v[92:95], v[168:171], v[234:237], v[92:95]
	v_mfma_f32_16x16x32_bf16 v[84:87], v[176:179], v[234:237], v[84:87]
	v_mfma_f32_16x16x32_bf16 v[76:79], v[168:171], v[242:245], v[76:79]
	v_mfma_f32_16x16x32_bf16 v[68:71], v[176:179], v[242:245], v[68:71]
	s_setprio 0
	s_setprio 1
	v_mfma_f32_16x16x32_bf16 v[120:123], v[180:183], v[214:217], v[120:123]
	v_mfma_f32_16x16x32_bf16 v[112:115], v[188:191], v[214:217], v[112:115]
	v_mfma_f32_16x16x32_bf16 v[104:107], v[180:183], v[222:225], v[104:107]
	v_mfma_f32_16x16x32_bf16 v[96:99], v[188:191], v[222:225], v[96:99]
	v_mfma_f32_16x16x32_bf16 v[88:91], v[180:183], v[230:233], v[88:91]
	v_mfma_f32_16x16x32_bf16 v[80:83], v[188:191], v[230:233], v[80:83]
	v_mfma_f32_16x16x32_bf16 v[72:75], v[180:183], v[238:241], v[72:75]
	v_mfma_f32_16x16x32_bf16 v[64:67], v[188:191], v[238:241], v[64:67]
	v_mfma_f32_16x16x32_bf16 v[120:123], v[184:187], v[218:221], v[120:123]
	v_mfma_f32_16x16x32_bf16 v[112:115], v[210:213], v[218:221], v[112:115]
	v_mfma_f32_16x16x32_bf16 v[104:107], v[184:187], v[226:229], v[104:107]
	v_mfma_f32_16x16x32_bf16 v[96:99], v[210:213], v[226:229], v[96:99]
	v_mfma_f32_16x16x32_bf16 v[88:91], v[184:187], v[234:237], v[88:91]
	v_mfma_f32_16x16x32_bf16 v[80:83], v[210:213], v[234:237], v[80:83]
	v_mfma_f32_16x16x32_bf16 v[72:75], v[184:187], v[242:245], v[72:75]
	v_mfma_f32_16x16x32_bf16 v[64:67], v[210:213], v[242:245], v[64:67]
	s_setprio 0
	s_barrier
	s_mov_b32 m0, s27
	v_lshl_add_u64 v[162:163], s[16:17], 0, v[132:133]
	s_add_u32 s54, s16, 0x40000
	ds_read_b128 v[214:217], v165 offset:16384
	ds_read_b128 v[218:221], v165 offset:17408
	ds_read_b128 v[222:225], v165 offset:18432
	ds_read_b128 v[226:229], v165 offset:19456
	ds_read_b128 v[230:233], v165 offset:20480
	ds_read_b128 v[234:237], v165 offset:21504
	ds_read_b128 v[238:241], v165 offset:22528
	ds_read_b128 v[242:245], v165 offset:23552
	global_load_lds_dwordx4 v[162:163], off
	v_lshl_add_u64 v[246:247], s[16:17], 0, v[128:129]
	s_mov_b32 m0, s28
	s_addc_u32 s55, s17, 0
	global_load_lds_dwordx4 v[246:247], off
	v_lshl_add_u64 v[248:249], s[54:55], 0, v[132:133]
	s_mov_b32 m0, s29
	v_lshl_add_u64 v[250:251], s[18:19], 0, v[130:131]
	global_load_lds_dwordx4 v[248:249], off
	v_lshl_add_u64 v[248:249], s[54:55], 0, v[128:129]
	s_mov_b32 m0, s30
	s_nop 0
	global_load_lds_dwordx4 v[248:249], off
	v_lshl_add_u64 v[248:249], s[18:19], 0, v[134:135]
	s_mov_b32 m0, s22
	s_nop 0
	global_load_lds_dwordx4 v[248:249], off
	s_mov_b32 m0, s31
	s_nop 0
	global_load_lds_dwordx4 v[250:251], off
	s_waitcnt vmcnt(16)
	s_waitcnt lgkmcnt(0)
	s_barrier
	s_setprio 1
	s_waitcnt lgkmcnt(0)
	v_mfma_f32_16x16x32_bf16 v[60:63], v[140:143], v[214:217], v[60:63]
	v_mfma_f32_16x16x32_bf16 v[52:55], v[172:175], v[214:217], v[52:55]
	v_mfma_f32_16x16x32_bf16 v[44:47], v[140:143], v[222:225], v[44:47]
	v_mfma_f32_16x16x32_bf16 v[36:39], v[172:175], v[222:225], v[36:39]
	v_mfma_f32_16x16x32_bf16 v[28:31], v[140:143], v[230:233], v[28:31]
	v_mfma_f32_16x16x32_bf16 v[20:23], v[172:175], v[230:233], v[20:23]
	v_mfma_f32_16x16x32_bf16 v[12:15], v[140:143], v[238:241], v[12:15]
	v_mfma_f32_16x16x32_bf16 v[4:7], v[172:175], v[238:241], v[4:7]
	v_mfma_f32_16x16x32_bf16 v[60:63], v[168:171], v[218:221], v[60:63]
	v_mfma_f32_16x16x32_bf16 v[52:55], v[176:179], v[218:221], v[52:55]
	v_mfma_f32_16x16x32_bf16 v[44:47], v[168:171], v[226:229], v[44:47]
	v_mfma_f32_16x16x32_bf16 v[36:39], v[176:179], v[226:229], v[36:39]
	v_mfma_f32_16x16x32_bf16 v[28:31], v[168:171], v[234:237], v[28:31]
	v_mfma_f32_16x16x32_bf16 v[20:23], v[176:179], v[234:237], v[20:23]
	v_mfma_f32_16x16x32_bf16 v[12:15], v[168:171], v[242:245], v[12:15]
	v_mfma_f32_16x16x32_bf16 v[4:7], v[176:179], v[242:245], v[4:7]
	s_setprio 0
	s_setprio 1
	v_mfma_f32_16x16x32_bf16 v[56:59], v[180:183], v[214:217], v[56:59]
	v_mfma_f32_16x16x32_bf16 v[48:51], v[188:191], v[214:217], v[48:51]
	v_mfma_f32_16x16x32_bf16 v[40:43], v[180:183], v[222:225], v[40:43]
	v_mfma_f32_16x16x32_bf16 v[32:35], v[188:191], v[222:225], v[32:35]
	v_mfma_f32_16x16x32_bf16 v[24:27], v[180:183], v[230:233], v[24:27]
	v_mfma_f32_16x16x32_bf16 v[16:19], v[188:191], v[230:233], v[16:19]
	v_mfma_f32_16x16x32_bf16 v[8:11], v[180:183], v[238:241], v[8:11]
	v_mfma_f32_16x16x32_bf16 v[0:3], v[188:191], v[238:241], v[0:3]
	v_mfma_f32_16x16x32_bf16 v[56:59], v[184:187], v[218:221], v[56:59]
	v_mfma_f32_16x16x32_bf16 v[48:51], v[210:213], v[218:221], v[48:51]
	v_mfma_f32_16x16x32_bf16 v[40:43], v[184:187], v[226:229], v[40:43]
	v_mfma_f32_16x16x32_bf16 v[32:35], v[210:213], v[226:229], v[32:35]
	v_mfma_f32_16x16x32_bf16 v[24:27], v[184:187], v[234:237], v[24:27]
	v_mfma_f32_16x16x32_bf16 v[16:19], v[210:213], v[234:237], v[16:19]
	v_mfma_f32_16x16x32_bf16 v[8:11], v[184:187], v[242:245], v[8:11]
	v_mfma_f32_16x16x32_bf16 v[0:3], v[210:213], v[242:245], v[0:3]
	s_setprio 0
	s_barrier
; #define PG8_STAGE(bufoff, gbase, voff) do { _Pragma("unroll") for (int _i = 0; _i < 2; ++_i) \
;         __builtin_amdgcn_global_load_lds((const unsigned*)((const char*)(gbase) + (voff)[_i]), (PG8_LAS unsigned*)(lds + (bufoff) + ldsw + _i * 8192), 16, 0, 0); } while (0)
; #define PG8_LDA(dst, b, h) do { _Pragma("unroll") for (int m = 0; m < 4; ++m) _Pragma("unroll") for (int k = 0; k < 2; ++k) dst[m][k] = *(const PG8_LAS bf16x8*)(lds + PG8_SA(b, h) + aoff + m * 2048 + k * 1024); } while (0)
; #define PG8_LDB(dst, b, h) do { _Pragma("unroll") for (int n = 0; n < 2; ++n) _Pragma("unroll") for (int k = 0; k < 2; ++k) dst[n][k] = *(const PG8_LAS bf16x8*)(lds + PG8_SB(b, h) + boff + n * 2048 + k * 1024); } while (0)
; #define PG8_MMA(ai, bj, At, Bt) do { __builtin_amdgcn_s_setprio(1); _Pragma("unroll") for (int m = 0; m < 4; ++m) _Pragma("unroll") for (int n = 0; n < 2; ++n) _Pragma("unroll") for (int k = 0; k < 2; ++k) \
;         acc[ai][bj][m][n] = __builtin_amdgcn_mfma_f32_16x16x32_bf16(Bt[n][k], At[m][k], acc[ai][bj][m][n], 0, 0, 0); __builtin_amdgcn_s_setprio(0); } while (0)
; #define PG8_WAIT_V(n) asm volatile("s_waitcnt vmcnt(" #n ")" ::: "memory")
; #define PG8_WAIT_L(n) asm volatile("s_waitcnt lgkmcnt(" #n ")" ::: "memory")
; #define PG8_BAR __builtin_amdgcn_s_barrier()
; #define PG8_SCHED __builtin_amdgcn_sched_barrier(0)
; template <class Epi, class Sched, bool ALIGN_EPI = false, bool SP2 = false>
; __device__ __forceinline__ void gemm_phase(PG8_LAS unsigned char* lds, const Gemm g, const Sched& S, const Epi& E) {
;     ...
;             PG8_WAIT_V(8); PG8_WAIT_L(0); PG8_BAR; PG8_MMA(1, 0, At, B0); PG8_MMA(1, 1, At, B1); PG8_BAR; PG8_SCHED;
;             PG8_LDB(B0, 1, 0); PG8_LDB(B1, 1, 1); PG8_SCHED; PG8_LDA(At, 1, 0); PG8_STAGE(PG8_SA(0, 1), a2 + hstep, voffA);
;             PG8_WAIT_V(8); PG8_WAIT_L(0); PG8_BAR; PG8_MMA(0, 0, At, B0); PG8_MMA(0, 1, At, B1); PG8_BAR; PG8_SCHED;
;             PG8_LDA(At, 1, 1); PG8_STAGE(PG8_SB(1, 0), b3, voffB); PG8_STAGE(PG8_SB(1, 1), b3 + hstep, voffB); PG8_STAGE(PG8_SA(1, 0), a3, voffA);
	v_or_b32_e32 v140, 0x18000, v166
	v_add_u32_e32 v167, 0x18400, v166
	ds_read_b128 v[140:143], v140
	ds_read_b128 v[168:171], v167
	v_add_u32_e32 v167, 0x18800, v166
	v_add_u32_e32 v176, 0x18c00, v166
	ds_read_b128 v[172:175], v167
	ds_read_b128 v[176:179], v176
	v_or_b32_e32 v167, 0x1c000, v166
	v_add_u32_e32 v184, 0x1c400, v166
	ds_read_b128 v[180:183], v167
	ds_read_b128 v[184:187], v184
	v_add_u32_e32 v167, 0x1c800, v166
	v_add_u32_e32 v208, 0x1cc00, v166
	ds_read_b128 v[188:191], v167
	ds_read_b128 v[210:213], v208
	s_add_u32 s18, s18, 0x40000
	s_addc_u32 s19, s19, 0
	s_mov_b32 m0, s33
	v_lshl_add_u64 v[208:209], s[18:19], 0, v[134:135]
	ds_read_b128 v[214:217], v165 offset:32768
	ds_read_b128 v[218:221], v165 offset:33792
	ds_read_b128 v[222:225], v165 offset:34816
	ds_read_b128 v[226:229], v165 offset:35840
	ds_read_b128 v[230:233], v165 offset:36864
	ds_read_b128 v[234:237], v165 offset:37888
	ds_read_b128 v[238:241], v165 offset:38912
	ds_read_b128 v[242:245], v165 offset:39936
	global_load_lds_dwordx4 v[208:209], off
	v_lshl_add_u64 v[208:209], s[18:19], 0, v[130:131]
	s_mov_b32 m0, s34
	s_nop 0
	global_load_lds_dwordx4 v[208:209], off
	s_waitcnt vmcnt(16)
	s_waitcnt lgkmcnt(0)
	s_barrier
	s_setprio 1
	s_waitcnt lgkmcnt(0)
	v_mfma_f32_16x16x32_bf16 v[124:127], v[140:143], v[214:217], v[124:127]
	v_mfma_f32_16x16x32_bf16 v[116:119], v[172:175], v[214:217], v[116:119]
	v_mfma_f32_16x16x32_bf16 v[108:111], v[140:143], v[222:225], v[108:111]
	v_mfma_f32_16x16x32_bf16 v[100:103], v[172:175], v[222:225], v[100:103]
	v_mfma_f32_16x16x32_bf16 v[92:95], v[140:143], v[230:233], v[92:95]
	v_mfma_f32_16x16x32_bf16 v[84:87], v[172:175], v[230:233], v[84:87]
	v_mfma_f32_16x16x32_bf16 v[76:79], v[140:143], v[238:241], v[76:79]
	v_mfma_f32_16x16x32_bf16 v[68:71], v[172:175], v[238:241], v[68:71]
	v_mfma_f32_16x16x32_bf16 v[124:127], v[168:171], v[218:221], v[124:127]
	v_mfma_f32_16x16x32_bf16 v[116:119], v[176:179], v[218:221], v[116:119]
	v_mfma_f32_16x16x32_bf16 v[108:111], v[168:171], v[226:229], v[108:111]
	v_mfma_f32_16x16x32_bf16 v[100:103], v[176:179], v[226:229], v[100:103]
	v_mfma_f32_16x16x32_bf16 v[92:95], v[168:171], v[234:237], v[92:95]
	v_mfma_f32_16x16x32_bf16 v[84:87], v[176:179], v[234:237], v[84:87]
	v_mfma_f32_16x16x32_bf16 v[76:79], v[168:171], v[242:245], v[76:79]
	v_mfma_f32_16x16x32_bf16 v[68:71], v[176:179], v[242:245], v[68:71]
	s_setprio 0
	s_setprio 1
	v_mfma_f32_16x16x32_bf16 v[120:123], v[180:183], v[214:217], v[120:123]
	v_mfma_f32_16x16x32_bf16 v[112:115], v[188:191], v[214:217], v[112:115]
	v_mfma_f32_16x16x32_bf16 v[104:107], v[180:183], v[222:225], v[104:107]
	v_mfma_f32_16x16x32_bf16 v[96:99], v[188:191], v[222:225], v[96:99]
	v_mfma_f32_16x16x32_bf16 v[88:91], v[180:183], v[230:233], v[88:91]
	v_mfma_f32_16x16x32_bf16 v[80:83], v[188:191], v[230:233], v[80:83]
	v_mfma_f32_16x16x32_bf16 v[72:75], v[180:183], v[238:241], v[72:75]
	v_mfma_f32_16x16x32_bf16 v[64:67], v[188:191], v[238:241], v[64:67]
	v_mfma_f32_16x16x32_bf16 v[120:123], v[184:187], v[218:221], v[120:123]
	v_mfma_f32_16x16x32_bf16 v[112:115], v[210:213], v[218:221], v[112:115]
	v_mfma_f32_16x16x32_bf16 v[104:107], v[184:187], v[226:229], v[104:107]
	v_mfma_f32_16x16x32_bf16 v[96:99], v[210:213], v[226:229], v[96:99]
	v_mfma_f32_16x16x32_bf16 v[88:91], v[184:187], v[234:237], v[88:91]
	v_mfma_f32_16x16x32_bf16 v[80:83], v[210:213], v[234:237], v[80:83]
	v_mfma_f32_16x16x32_bf16 v[72:75], v[184:187], v[242:245], v[72:75]
	v_mfma_f32_16x16x32_bf16 v[64:67], v[210:213], v[242:245], v[64:67]
	s_setprio 0
	s_barrier
	s_mov_b32 m0, s37
	v_lshl_add_u64 v[162:163], v[162:163], 0, s[94:95]
	s_add_u32 s16, s16, 0x40080
	ds_read_b128 v[214:217], v165 offset:49152
	ds_read_b128 v[218:221], v165 offset:50176
	ds_read_b128 v[222:225], v165 offset:51200
	ds_read_b128 v[226:229], v165 offset:52224
	ds_read_b128 v[230:233], v165 offset:53248
	ds_read_b128 v[234:237], v165 offset:54272
	ds_read_b128 v[238:241], v165 offset:55296
	ds_read_b128 v[242:245], v165 offset:56320
	global_load_lds_dwordx4 v[162:163], off
	v_lshl_add_u64 v[162:163], v[246:247], 0, s[94:95]
	s_mov_b32 m0, s38
	s_addc_u32 s17, s17, 0
	global_load_lds_dwordx4 v[162:163], off
	v_lshl_add_u64 v[162:163], s[16:17], 0, v[132:133]
	s_mov_b32 m0, s41
	s_nop 0
	global_load_lds_dwordx4 v[162:163], off
	v_lshl_add_u64 v[162:163], s[16:17], 0, v[128:129]
	s_mov_b32 m0, s42
	s_nop 0
	global_load_lds_dwordx4 v[162:163], off
	v_lshl_add_u64 v[162:163], v[248:249], 0, s[94:95]
	s_mov_b32 m0, s39
	s_nop 0
	global_load_lds_dwordx4 v[162:163], off
	v_lshl_add_u64 v[162:163], v[250:251], 0, s[94:95]
	s_mov_b32 m0, s40
	s_nop 0
	global_load_lds_dwordx4 v[162:163], off
	s_waitcnt vmcnt(8)
	s_waitcnt lgkmcnt(0)
	s_barrier
; #define PG8_STAGE(bufoff, gbase, voff) do { _Pragma("unroll") for (int _i = 0; _i < 2; ++_i) \
;         __builtin_amdgcn_global_load_lds((const unsigned*)((const char*)(gbase) + (voff)[_i]), (PG8_LAS unsigned*)(lds + (bufoff) + ldsw + _i * 8192), 16, 0, 0); } while (0)
; #define PG8_LDA(dst, b, h) do { _Pragma("unroll") for (int m = 0; m < 4; ++m) _Pragma("unroll") for (int k = 0; k < 2; ++k) dst[m][k] = *(const PG8_LAS bf16x8*)(lds + PG8_SA(b, h) + aoff + m * 2048 + k * 1024); } while (0)
; #define PG8_LDB(dst, b, h) do { _Pragma("unroll") for (int n = 0; n < 2; ++n) _Pragma("unroll") for (int k = 0; k < 2; ++k) dst[n][k] = *(const PG8_LAS bf16x8*)(lds + PG8_SB(b, h) + boff + n * 2048 + k * 1024); } while (0)
; #define PG8_MMA(ai, bj, At, Bt) do { __builtin_amdgcn_s_setprio(1); _Pragma("unroll") for (int m = 0; m < 4; ++m) _Pragma("unroll") for (int n = 0; n < 2; ++n) _Pragma("unroll") for (int k = 0; k < 2; ++k) \
;         acc[ai][bj][m][n] = __builtin_amdgcn_mfma_f32_16x16x32_bf16(Bt[n][k], At[m][k], acc[ai][bj][m][n], 0, 0, 0); __builtin_amdgcn_s_setprio(0); } while (0)
; #define PG8_WAIT_V(n) asm volatile("s_waitcnt vmcnt(" #n ")" ::: "memory")
; template <class Epi, class Sched, bool ALIGN_EPI = false, bool SP2 = false>
; __device__ __forceinline__ void gemm_phase(PG8_LAS unsigned char* lds, const Gemm g, const Sched& S, const Epi& E) {
;     ...
;             PG8_LDB(B0, 0, 0); PG8_LDB(B1, 0, 1); PG8_SCHED; PG8_LDA(At, 0, 0); PG8_STAGE(PG8_SA(1, 1), a1 + hstep, voffA);
;             PG8_WAIT_V(8); PG8_WAIT_L(0); PG8_BAR; PG8_MMA(0, 0, At, B0); PG8_MMA(0, 1, At, B1); PG8_BAR; PG8_SCHED;
;             PG8_LDA(At, 0, 1); PG8_STAGE(PG8_SB(0, 0), b2, voffB); PG8_STAGE(PG8_SB(0, 1), b2 + hstep, voffB); PG8_STAGE(PG8_SA(0, 0), a2, voffA);
;             PG8_WAIT_V(8); PG8_WAIT_L(0); PG8_BAR; PG8_MMA(1, 0, At, B0); PG8_MMA(1, 1, At, B1); PG8_BAR; PG8_SCHED;
;             PG8_LDB(B0, 1, 0); PG8_LDB(B1, 1, 1); PG8_SCHED; PG8_LDA(At, 1, 0); PG8_STAGE(PG8_SA(0, 1), a2 + hstep, voffA);
;             PG8_WAIT_V(8); PG8_WAIT_L(0); PG8_BAR; PG8_MMA(0, 0, At, B0); PG8_MMA(0, 1, At, B1); PG8_BAR; PG8_SCHED;
;             PG8_LDA(At, 1, 1); PG8_STAGE(PG8_SB(1, 0), b3, voffB); PG8_STAGE(PG8_SB(1, 1), b3 + hstep, voffB); PG8_STAGE(PG8_SA(1, 0), a3, voffA);
;             PG8_WAIT_V(8); PG8_WAIT_L(0); PG8_BAR; PG8_MMA(1, 0, At, B0); PG8_MMA(1, 1, At, B1); PG8_BAR; PG8_SCHED;
	s_setprio 1
	s_waitcnt lgkmcnt(0)
	v_mfma_f32_16x16x32_bf16 v[60:63], v[140:143], v[214:217], v[60:63]
	v_mfma_f32_16x16x32_bf16 v[52:55], v[172:175], v[214:217], v[52:55]
	v_mfma_f32_16x16x32_bf16 v[44:47], v[140:143], v[222:225], v[44:47]
	v_mfma_f32_16x16x32_bf16 v[36:39], v[172:175], v[222:225], v[36:39]
	v_mfma_f32_16x16x32_bf16 v[28:31], v[140:143], v[230:233], v[28:31]
	v_mfma_f32_16x16x32_bf16 v[20:23], v[172:175], v[230:233], v[20:23]
	v_mfma_f32_16x16x32_bf16 v[12:15], v[140:143], v[238:241], v[12:15]
	v_mfma_f32_16x16x32_bf16 v[4:7], v[172:175], v[238:241], v[4:7]
	v_mfma_f32_16x16x32_bf16 v[60:63], v[168:171], v[218:221], v[60:63]
	v_mfma_f32_16x16x32_bf16 v[52:55], v[176:179], v[218:221], v[52:55]
	v_mfma_f32_16x16x32_bf16 v[44:47], v[168:171], v[226:229], v[44:47]
	v_mfma_f32_16x16x32_bf16 v[36:39], v[176:179], v[226:229], v[36:39]
	v_mfma_f32_16x16x32_bf16 v[28:31], v[168:171], v[234:237], v[28:31]
	v_mfma_f32_16x16x32_bf16 v[20:23], v[176:179], v[234:237], v[20:23]
	v_mfma_f32_16x16x32_bf16 v[12:15], v[168:171], v[242:245], v[12:15]
	v_mfma_f32_16x16x32_bf16 v[4:7], v[176:179], v[242:245], v[4:7]
	s_setprio 0
	s_setprio 1
	v_mfma_f32_16x16x32_bf16 v[56:59], v[180:183], v[214:217], v[56:59]
	v_mfma_f32_16x16x32_bf16 v[48:51], v[188:191], v[214:217], v[48:51]
	v_mfma_f32_16x16x32_bf16 v[40:43], v[180:183], v[222:225], v[40:43]
	v_mfma_f32_16x16x32_bf16 v[32:35], v[188:191], v[222:225], v[32:35]
	v_mfma_f32_16x16x32_bf16 v[24:27], v[180:183], v[230:233], v[24:27]
	v_mfma_f32_16x16x32_bf16 v[16:19], v[188:191], v[230:233], v[16:19]
	v_mfma_f32_16x16x32_bf16 v[8:11], v[180:183], v[238:241], v[8:11]
	v_mfma_f32_16x16x32_bf16 v[0:3], v[188:191], v[238:241], v[0:3]
	v_mfma_f32_16x16x32_bf16 v[56:59], v[184:187], v[218:221], v[56:59]
	v_mfma_f32_16x16x32_bf16 v[48:51], v[210:213], v[218:221], v[48:51]
	v_mfma_f32_16x16x32_bf16 v[40:43], v[184:187], v[226:229], v[40:43]
	v_mfma_f32_16x16x32_bf16 v[32:35], v[210:213], v[226:229], v[32:35]
	v_mfma_f32_16x16x32_bf16 v[24:27], v[184:187], v[234:237], v[24:27]
	v_mfma_f32_16x16x32_bf16 v[16:19], v[210:213], v[234:237], v[16:19]
	v_mfma_f32_16x16x32_bf16 v[8:11], v[184:187], v[242:245], v[8:11]
	v_mfma_f32_16x16x32_bf16 v[0:3], v[210:213], v[242:245], v[0:3]
	s_setprio 0
	s_barrier
	s_add_i32 s53, s53, 2
	s_add_u32 s14, s14, 0x100
	s_addc_u32 s15, s15, 0
	s_add_u32 s51, s51, 0x100
	s_addc_u32 s52, s52, 0
.LBB0_446:
	v_or_b32_e32 v140, 0x10000, v166
	v_add_u32_e32 v162, 0x10400, v166
	ds_read_b128 v[140:143], v140
	ds_read_b128 v[168:171], v162
	v_add_u32_e32 v162, 0x10800, v166
	v_add_u32_e32 v163, 0x10c00, v166
	ds_read_b128 v[172:175], v162
	ds_read_b128 v[176:179], v163
	v_or_b32_e32 v162, 0x14000, v166
	v_add_u32_e32 v163, 0x14400, v166
	ds_read_b128 v[180:183], v162
	ds_read_b128 v[184:187], v163
	v_add_u32_e32 v162, 0x14800, v166
	v_add_u32_e32 v163, 0x14c00, v166
	ds_read_b128 v[188:191], v162
	ds_read_b128 v[210:213], v163
	s_add_u32 s16, s14, 0xfffc0080
	s_addc_u32 s17, s15, -1
	s_cmp_eq_u32 s53, 12
	s_cselect_b32 s19, s7, s17
	s_cselect_b32 s18, s49, s16
	s_cselect_b32 s17, s5, s52
	s_cselect_b32 s16, s50, s51
	s_mov_b32 m0, s43
	v_lshl_add_u64 v[162:163], s[14:15], 0, v[136:137]
	ds_read_b128 v[214:217], v165
	ds_read_b128 v[218:221], v165 offset:1024
	ds_read_b128 v[222:225], v165 offset:2048
	ds_read_b128 v[226:229], v165 offset:3072
	ds_read_b128 v[230:233], v165 offset:4096
	ds_read_b128 v[234:237], v165 offset:5120
	ds_read_b128 v[238:241], v165 offset:6144
	ds_read_b128 v[242:245], v165 offset:7168
	global_load_lds_dwordx4 v[162:163], off
	v_lshl_add_u64 v[162:163], s[14:15], 0, v[138:139]
	s_mov_b32 m0, s44
	s_nop 0
	global_load_lds_dwordx4 v[162:163], off
	s_waitcnt vmcnt(8)
	s_waitcnt lgkmcnt(0)
	s_barrier
	s_setprio 1
	s_waitcnt lgkmcnt(0)
	v_mfma_f32_16x16x32_bf16 v[124:127], v[140:143], v[214:217], v[124:127]
	v_mfma_f32_16x16x32_bf16 v[116:119], v[172:175], v[214:217], v[116:119]
	v_mfma_f32_16x16x32_bf16 v[108:111], v[140:143], v[222:225], v[108:111]
	v_mfma_f32_16x16x32_bf16 v[100:103], v[172:175], v[222:225], v[100:103]
	v_mfma_f32_16x16x32_bf16 v[92:95], v[140:143], v[230:233], v[92:95]
	v_mfma_f32_16x16x32_bf16 v[84:87], v[172:175], v[230:233], v[84:87]
	v_mfma_f32_16x16x32_bf16 v[76:79], v[140:143], v[238:241], v[76:79]
	v_mfma_f32_16x16x32_bf16 v[68:71], v[172:175], v[238:241], v[68:71]
	v_mfma_f32_16x16x32_bf16 v[124:127], v[168:171], v[218:221], v[124:127]
	v_mfma_f32_16x16x32_bf16 v[116:119], v[176:179], v[218:221], v[116:119]
	v_mfma_f32_16x16x32_bf16 v[108:111], v[168:171], v[226:229], v[108:111]
	v_mfma_f32_16x16x32_bf16 v[100:103], v[176:179], v[226:229], v[100:103]
	v_mfma_f32_16x16x32_bf16 v[92:95], v[168:171], v[234:237], v[92:95]
	v_mfma_f32_16x16x32_bf16 v[84:87], v[176:179], v[234:237], v[84:87]
	v_mfma_f32_16x16x32_bf16 v[76:79], v[168:171], v[242:245], v[76:79]
	v_mfma_f32_16x16x32_bf16 v[68:71], v[176:179], v[242:245], v[68:71]
	s_setprio 0
	s_setprio 1
	v_mfma_f32_16x16x32_bf16 v[120:123], v[180:183], v[214:217], v[120:123]
	v_mfma_f32_16x16x32_bf16 v[112:115], v[188:191], v[214:217], v[112:115]
	v_mfma_f32_16x16x32_bf16 v[104:107], v[180:183], v[222:225], v[104:107]
	v_mfma_f32_16x16x32_bf16 v[96:99], v[188:191], v[222:225], v[96:99]
	v_mfma_f32_16x16x32_bf16 v[88:91], v[180:183], v[230:233], v[88:91]
	v_mfma_f32_16x16x32_bf16 v[80:83], v[188:191], v[230:233], v[80:83]
	v_mfma_f32_16x16x32_bf16 v[72:75], v[180:183], v[238:241], v[72:75]
	v_mfma_f32_16x16x32_bf16 v[64:67], v[188:191], v[238:241], v[64:67]
	v_mfma_f32_16x16x32_bf16 v[120:123], v[184:187], v[218:221], v[120:123]
	v_mfma_f32_16x16x32_bf16 v[112:115], v[210:213], v[218:221], v[112:115]
	v_mfma_f32_16x16x32_bf16 v[104:107], v[184:187], v[226:229], v[104:107]
	v_mfma_f32_16x16x32_bf16 v[96:99], v[210:213], v[226:229], v[96:99]
	v_mfma_f32_16x16x32_bf16 v[88:91], v[184:187], v[234:237], v[88:91]
	v_mfma_f32_16x16x32_bf16 v[80:83], v[210:213], v[234:237], v[80:83]
	v_mfma_f32_16x16x32_bf16 v[72:75], v[184:187], v[242:245], v[72:75]
	v_mfma_f32_16x16x32_bf16 v[64:67], v[210:213], v[242:245], v[64:67]
	s_setprio 0
	s_barrier
; #define PG8_STAGE(bufoff, gbase, voff) do { _Pragma("unroll") for (int _i = 0; _i < 2; ++_i) \
;         __builtin_amdgcn_global_load_lds((const unsigned*)((const char*)(gbase) + (voff)[_i]), (PG8_LAS unsigned*)(lds + (bufoff) + ldsw + _i * 8192), 16, 0, 0); } while (0)
; #define PG8_LDA(dst, b, h) do { _Pragma("unroll") for (int m = 0; m < 4; ++m) _Pragma("unroll") for (int k = 0; k < 2; ++k) dst[m][k] = *(const PG8_LAS bf16x8*)(lds + PG8_SA(b, h) + aoff + m * 2048 + k * 1024); } while (0)
; #define PG8_LDB(dst, b, h) do { _Pragma("unroll") for (int n = 0; n < 2; ++n) _Pragma("unroll") for (int k = 0; k < 2; ++k) dst[n][k] = *(const PG8_LAS bf16x8*)(lds + PG8_SB(b, h) + boff + n * 2048 + k * 1024); } while (0)
; #define PG8_MMA(ai, bj, At, Bt) do { __builtin_amdgcn_s_setprio(1); _Pragma("unroll") for (int m = 0; m < 4; ++m) _Pragma("unroll") for (int n = 0; n < 2; ++n) _Pragma("unroll") for (int k = 0; k < 2; ++k) \
;         acc[ai][bj][m][n] = __builtin_amdgcn_mfma_f32_16x16x32_bf16(Bt[n][k], At[m][k], acc[ai][bj][m][n], 0, 0, 0); __builtin_amdgcn_s_setprio(0); } while (0)
; #define PG8_WAIT_V(n) asm volatile("s_waitcnt vmcnt(" #n ")" ::: "memory")
; #define PG8_WAIT_L(n) asm volatile("s_waitcnt lgkmcnt(" #n ")" ::: "memory")
; #define PG8_BAR __builtin_amdgcn_s_barrier()
; #define PG8_SCHED __builtin_amdgcn_sched_barrier(0)
; template <class Epi, class Sched, bool ALIGN_EPI = false, bool SP2 = false>
; __device__ __forceinline__ void gemm_phase(PG8_LAS unsigned char* lds, const Gemm g, const Sched& S, const Epi& E) {
;     ...
;             PG8_LDA(At, 0, 1); PG8_STAGE(PG8_SB(0, 0), b2, voffB); PG8_STAGE(PG8_SB(0, 1), b2 + hstep, voffB); PG8_STAGE(PG8_SA(0, 0), a2, voffA);
;             PG8_WAIT_V(8); PG8_WAIT_L(0); PG8_BAR; PG8_MMA(1, 0, At, B0); PG8_MMA(1, 1, At, B1); PG8_BAR; PG8_SCHED;
;             PG8_LDB(B0, 1, 0); PG8_LDB(B1, 1, 1); PG8_SCHED; PG8_LDA(At, 1, 0); PG8_STAGE(PG8_SA(0, 1), a2 + hstep, voffA);
;             PG8_WAIT_V(8); PG8_WAIT_L(0); PG8_BAR; PG8_MMA(0, 0, At, B0); PG8_MMA(0, 1, At, B1); PG8_BAR; PG8_SCHED;
	s_mov_b32 m0, s27
	v_lshl_add_u64 v[162:163], s[16:17], 0, v[132:133]
	s_add_u32 s54, s16, 0x40000
	ds_read_b128 v[214:217], v165 offset:16384
	ds_read_b128 v[218:221], v165 offset:17408
	ds_read_b128 v[222:225], v165 offset:18432
	ds_read_b128 v[226:229], v165 offset:19456
	ds_read_b128 v[230:233], v165 offset:20480
	ds_read_b128 v[234:237], v165 offset:21504
	ds_read_b128 v[238:241], v165 offset:22528
	ds_read_b128 v[242:245], v165 offset:23552
	global_load_lds_dwordx4 v[162:163], off
	v_lshl_add_u64 v[246:247], s[16:17], 0, v[128:129]
	s_mov_b32 m0, s28
	s_addc_u32 s55, s17, 0
	global_load_lds_dwordx4 v[246:247], off
	v_lshl_add_u64 v[248:249], s[54:55], 0, v[132:133]
	s_mov_b32 m0, s29
	v_lshl_add_u64 v[250:251], s[18:19], 0, v[130:131]
	global_load_lds_dwordx4 v[248:249], off
	v_lshl_add_u64 v[248:249], s[54:55], 0, v[128:129]
	s_mov_b32 m0, s30
	s_nop 0
	global_load_lds_dwordx4 v[248:249], off
	v_lshl_add_u64 v[248:249], s[18:19], 0, v[134:135]
	s_mov_b32 m0, s22
	s_nop 0
	global_load_lds_dwordx4 v[248:249], off
	s_mov_b32 m0, s31
	s_nop 0
	global_load_lds_dwordx4 v[250:251], off
	s_waitcnt vmcnt(8)
	s_waitcnt lgkmcnt(0)
	s_barrier
	s_setprio 1
	s_waitcnt lgkmcnt(0)
	v_mfma_f32_16x16x32_bf16 v[60:63], v[140:143], v[214:217], v[60:63]
	v_mfma_f32_16x16x32_bf16 v[52:55], v[172:175], v[214:217], v[52:55]
	v_mfma_f32_16x16x32_bf16 v[44:47], v[140:143], v[222:225], v[44:47]
	v_mfma_f32_16x16x32_bf16 v[36:39], v[172:175], v[222:225], v[36:39]
	v_mfma_f32_16x16x32_bf16 v[28:31], v[140:143], v[230:233], v[28:31]
	v_mfma_f32_16x16x32_bf16 v[20:23], v[172:175], v[230:233], v[20:23]
	v_mfma_f32_16x16x32_bf16 v[12:15], v[140:143], v[238:241], v[12:15]
	v_mfma_f32_16x16x32_bf16 v[4:7], v[172:175], v[238:241], v[4:7]
	v_mfma_f32_16x16x32_bf16 v[60:63], v[168:171], v[218:221], v[60:63]
	v_mfma_f32_16x16x32_bf16 v[52:55], v[176:179], v[218:221], v[52:55]
	v_mfma_f32_16x16x32_bf16 v[44:47], v[168:171], v[226:229], v[44:47]
	v_mfma_f32_16x16x32_bf16 v[36:39], v[176:179], v[226:229], v[36:39]
	v_mfma_f32_16x16x32_bf16 v[28:31], v[168:171], v[234:237], v[28:31]
	v_mfma_f32_16x16x32_bf16 v[20:23], v[176:179], v[234:237], v[20:23]
	v_mfma_f32_16x16x32_bf16 v[12:15], v[168:171], v[242:245], v[12:15]
	v_mfma_f32_16x16x32_bf16 v[4:7], v[176:179], v[242:245], v[4:7]
	s_setprio 0
	s_setprio 1
	v_mfma_f32_16x16x32_bf16 v[56:59], v[180:183], v[214:217], v[56:59]
	v_mfma_f32_16x16x32_bf16 v[48:51], v[188:191], v[214:217], v[48:51]
	v_mfma_f32_16x16x32_bf16 v[40:43], v[180:183], v[222:225], v[40:43]
	v_mfma_f32_16x16x32_bf16 v[32:35], v[188:191], v[222:225], v[32:35]
	v_mfma_f32_16x16x32_bf16 v[24:27], v[180:183], v[230:233], v[24:27]
	v_mfma_f32_16x16x32_bf16 v[16:19], v[188:191], v[230:233], v[16:19]
	v_mfma_f32_16x16x32_bf16 v[8:11], v[180:183], v[238:241], v[8:11]
	v_mfma_f32_16x16x32_bf16 v[0:3], v[188:191], v[238:241], v[0:3]
	v_mfma_f32_16x16x32_bf16 v[56:59], v[184:187], v[218:221], v[56:59]
	v_mfma_f32_16x16x32_bf16 v[48:51], v[210:213], v[218:221], v[48:51]
	v_mfma_f32_16x16x32_bf16 v[40:43], v[184:187], v[226:229], v[40:43]
	v_mfma_f32_16x16x32_bf16 v[32:35], v[210:213], v[226:229], v[32:35]
	v_mfma_f32_16x16x32_bf16 v[24:27], v[184:187], v[234:237], v[24:27]
	v_mfma_f32_16x16x32_bf16 v[16:19], v[210:213], v[234:237], v[16:19]
	v_mfma_f32_16x16x32_bf16 v[8:11], v[184:187], v[242:245], v[8:11]
	v_mfma_f32_16x16x32_bf16 v[0:3], v[210:213], v[242:245], v[0:3]
	s_setprio 0
	s_barrier
	v_or_b32_e32 v140, 0x18000, v166
	v_add_u32_e32 v167, 0x18400, v166
	ds_read_b128 v[140:143], v140
	ds_read_b128 v[168:171], v167
	v_add_u32_e32 v167, 0x18800, v166
	v_add_u32_e32 v176, 0x18c00, v166
	ds_read_b128 v[172:175], v167
	ds_read_b128 v[176:179], v176
	v_or_b32_e32 v167, 0x1c000, v166
	v_add_u32_e32 v184, 0x1c400, v166
	ds_read_b128 v[180:183], v167
	ds_read_b128 v[184:187], v184
	v_add_u32_e32 v167, 0x1c800, v166
	v_add_u32_e32 v208, 0x1cc00, v166
	ds_read_b128 v[188:191], v167
	ds_read_b128 v[210:213], v208
	s_add_u32 s18, s18, 0x40000
	s_addc_u32 s19, s19, 0
	s_mov_b32 m0, s33
	v_lshl_add_u64 v[208:209], s[18:19], 0, v[134:135]
	ds_read_b128 v[214:217], v165 offset:32768
	ds_read_b128 v[218:221], v165 offset:33792
	ds_read_b128 v[222:225], v165 offset:34816
	ds_read_b128 v[226:229], v165 offset:35840
	ds_read_b128 v[230:233], v165 offset:36864
	ds_read_b128 v[234:237], v165 offset:37888
	ds_read_b128 v[238:241], v165 offset:38912
	ds_read_b128 v[242:245], v165 offset:39936
	global_load_lds_dwordx4 v[208:209], off
	v_lshl_add_u64 v[208:209], s[18:19], 0, v[130:131]
	s_mov_b32 m0, s34
	s_nop 0
	global_load_lds_dwordx4 v[208:209], off
	s_waitcnt vmcnt(8)
	s_waitcnt lgkmcnt(0)
	s_barrier
; #define PG8_STAGE(bufoff, gbase, voff) do { _Pragma("unroll") for (int _i = 0; _i < 2; ++_i) \
;         __builtin_amdgcn_global_load_lds((const unsigned*)((const char*)(gbase) + (voff)[_i]), (PG8_LAS unsigned*)(lds + (bufoff) + ldsw + _i * 8192), 16, 0, 0); } while (0)
; #define PG8_LDA(dst, b, h) do { _Pragma("unroll") for (int m = 0; m < 4; ++m) _Pragma("unroll") for (int k = 0; k < 2; ++k) dst[m][k] = *(const PG8_LAS bf16x8*)(lds + PG8_SA(b, h) + aoff + m * 2048 + k * 1024); } while (0)
; #define PG8_LDB(dst, b, h) do { _Pragma("unroll") for (int n = 0; n < 2; ++n) _Pragma("unroll") for (int k = 0; k < 2; ++k) dst[n][k] = *(const PG8_LAS bf16x8*)(lds + PG8_SB(b, h) + boff + n * 2048 + k * 1024); } while (0)
; #define PG8_MMA(ai, bj, At, Bt) do { __builtin_amdgcn_s_setprio(1); _Pragma("unroll") for (int m = 0; m < 4; ++m) _Pragma("unroll") for (int n = 0; n < 2; ++n) _Pragma("unroll") for (int k = 0; k < 2; ++k) \
;         acc[ai][bj][m][n] = __builtin_amdgcn_mfma_f32_16x16x32_bf16(Bt[n][k], At[m][k], acc[ai][bj][m][n], 0, 0, 0); __builtin_amdgcn_s_setprio(0); } while (0)
; #define PG8_WAIT_V(n) asm volatile("s_waitcnt vmcnt(" #n ")" ::: "memory")
; #define PG8_WAIT_L(n) asm volatile("s_waitcnt lgkmcnt(" #n ")" ::: "memory")
; #define PG8_BAR __builtin_amdgcn_s_barrier()
; #define PG8_SCHED __builtin_amdgcn_sched_barrier(0)
; template <class Epi, class Sched, bool ALIGN_EPI = false, bool SP2 = false>
; __device__ __forceinline__ void gemm_phase(PG8_LAS unsigned char* lds, const Gemm g, const Sched& S, const Epi& E) {
;     ...
;             PG8_LDB(B0, 0, 0); PG8_LDB(B1, 0, 1); PG8_SCHED; PG8_LDA(At, 0, 0); PG8_STAGE(PG8_SA(1, 1), a1 + hstep, voffA);
;     ...
;             PG8_WAIT_V(8); PG8_WAIT_L(0); PG8_BAR; PG8_MMA(0, 0, At, B0); PG8_MMA(0, 1, At, B1); PG8_BAR; PG8_SCHED;
;             PG8_LDA(At, 1, 1); PG8_STAGE(PG8_SB(1, 0), b3, voffB); PG8_STAGE(PG8_SB(1, 1), b3 + hstep, voffB); PG8_STAGE(PG8_SA(1, 0), a3, voffA);
;             PG8_WAIT_V(8); PG8_WAIT_L(0); PG8_BAR; PG8_MMA(1, 0, At, B0); PG8_MMA(1, 1, At, B1); PG8_BAR; PG8_SCHED;
	s_setprio 1
	s_waitcnt lgkmcnt(0)
	v_mfma_f32_16x16x32_bf16 v[124:127], v[140:143], v[214:217], v[124:127]
	v_mfma_f32_16x16x32_bf16 v[116:119], v[172:175], v[214:217], v[116:119]
	v_mfma_f32_16x16x32_bf16 v[108:111], v[140:143], v[222:225], v[108:111]
	v_mfma_f32_16x16x32_bf16 v[100:103], v[172:175], v[222:225], v[100:103]
	v_mfma_f32_16x16x32_bf16 v[92:95], v[140:143], v[230:233], v[92:95]
	v_mfma_f32_16x16x32_bf16 v[84:87], v[172:175], v[230:233], v[84:87]
	v_mfma_f32_16x16x32_bf16 v[76:79], v[140:143], v[238:241], v[76:79]
	v_mfma_f32_16x16x32_bf16 v[68:71], v[172:175], v[238:241], v[68:71]
	v_mfma_f32_16x16x32_bf16 v[124:127], v[168:171], v[218:221], v[124:127]
	v_mfma_f32_16x16x32_bf16 v[116:119], v[176:179], v[218:221], v[116:119]
	v_mfma_f32_16x16x32_bf16 v[108:111], v[168:171], v[226:229], v[108:111]
	v_mfma_f32_16x16x32_bf16 v[100:103], v[176:179], v[226:229], v[100:103]
	v_mfma_f32_16x16x32_bf16 v[92:95], v[168:171], v[234:237], v[92:95]
	v_mfma_f32_16x16x32_bf16 v[84:87], v[176:179], v[234:237], v[84:87]
	v_mfma_f32_16x16x32_bf16 v[76:79], v[168:171], v[242:245], v[76:79]
	v_mfma_f32_16x16x32_bf16 v[68:71], v[176:179], v[242:245], v[68:71]
	s_setprio 0
	s_setprio 1
	v_mfma_f32_16x16x32_bf16 v[120:123], v[180:183], v[214:217], v[120:123]
	v_mfma_f32_16x16x32_bf16 v[112:115], v[188:191], v[214:217], v[112:115]
	v_mfma_f32_16x16x32_bf16 v[104:107], v[180:183], v[222:225], v[104:107]
	v_mfma_f32_16x16x32_bf16 v[96:99], v[188:191], v[222:225], v[96:99]
	v_mfma_f32_16x16x32_bf16 v[88:91], v[180:183], v[230:233], v[88:91]
	v_mfma_f32_16x16x32_bf16 v[80:83], v[188:191], v[230:233], v[80:83]
	v_mfma_f32_16x16x32_bf16 v[72:75], v[180:183], v[238:241], v[72:75]
	v_mfma_f32_16x16x32_bf16 v[64:67], v[188:191], v[238:241], v[64:67]
	v_mfma_f32_16x16x32_bf16 v[120:123], v[184:187], v[218:221], v[120:123]
	v_mfma_f32_16x16x32_bf16 v[112:115], v[210:213], v[218:221], v[112:115]
	v_mfma_f32_16x16x32_bf16 v[104:107], v[184:187], v[226:229], v[104:107]
	v_mfma_f32_16x16x32_bf16 v[96:99], v[210:213], v[226:229], v[96:99]
	v_mfma_f32_16x16x32_bf16 v[88:91], v[184:187], v[234:237], v[88:91]
	v_mfma_f32_16x16x32_bf16 v[80:83], v[210:213], v[234:237], v[80:83]
	v_mfma_f32_16x16x32_bf16 v[72:75], v[184:187], v[242:245], v[72:75]
	v_mfma_f32_16x16x32_bf16 v[64:67], v[210:213], v[242:245], v[64:67]
	s_setprio 0
	s_barrier
	s_mov_b32 m0, s37
	v_lshl_add_u64 v[162:163], v[162:163], 0, s[94:95]
	s_add_u32 s16, s16, 0x40080
	ds_read_b128 v[214:217], v165 offset:49152
	ds_read_b128 v[218:221], v165 offset:50176
	ds_read_b128 v[222:225], v165 offset:51200
	ds_read_b128 v[226:229], v165 offset:52224
	ds_read_b128 v[230:233], v165 offset:53248
	ds_read_b128 v[234:237], v165 offset:54272
	ds_read_b128 v[238:241], v165 offset:55296
	ds_read_b128 v[242:245], v165 offset:56320
	global_load_lds_dwordx4 v[162:163], off
	v_lshl_add_u64 v[162:163], v[246:247], 0, s[94:95]
	s_mov_b32 m0, s38
	s_addc_u32 s17, s17, 0
	global_load_lds_dwordx4 v[162:163], off
	v_lshl_add_u64 v[162:163], s[16:17], 0, v[132:133]
	s_mov_b32 m0, s41
	s_nop 0
	global_load_lds_dwordx4 v[162:163], off
	v_lshl_add_u64 v[162:163], s[16:17], 0, v[128:129]
	s_mov_b32 m0, s42
	s_nop 0
	global_load_lds_dwordx4 v[162:163], off
	v_lshl_add_u64 v[162:163], v[248:249], 0, s[94:95]
	s_mov_b32 m0, s39
	s_nop 0
	global_load_lds_dwordx4 v[162:163], off
	v_lshl_add_u64 v[162:163], v[250:251], 0, s[94:95]
	s_mov_b32 m0, s40
	s_nop 0
	global_load_lds_dwordx4 v[162:163], off
	s_waitcnt vmcnt(8)
	s_waitcnt lgkmcnt(0)
	s_barrier
	s_setprio 1
	s_waitcnt lgkmcnt(0)
	v_mfma_f32_16x16x32_bf16 v[60:63], v[140:143], v[214:217], v[60:63]
	v_mfma_f32_16x16x32_bf16 v[52:55], v[172:175], v[214:217], v[52:55]
	v_mfma_f32_16x16x32_bf16 v[44:47], v[140:143], v[222:225], v[44:47]
	v_mfma_f32_16x16x32_bf16 v[36:39], v[172:175], v[222:225], v[36:39]
	v_mfma_f32_16x16x32_bf16 v[28:31], v[140:143], v[230:233], v[28:31]
	v_mfma_f32_16x16x32_bf16 v[20:23], v[172:175], v[230:233], v[20:23]
	v_mfma_f32_16x16x32_bf16 v[12:15], v[140:143], v[238:241], v[12:15]
	v_mfma_f32_16x16x32_bf16 v[4:7], v[172:175], v[238:241], v[4:7]
	v_mfma_f32_16x16x32_bf16 v[60:63], v[168:171], v[218:221], v[60:63]
	v_mfma_f32_16x16x32_bf16 v[52:55], v[176:179], v[218:221], v[52:55]
	v_mfma_f32_16x16x32_bf16 v[44:47], v[168:171], v[226:229], v[44:47]
	v_mfma_f32_16x16x32_bf16 v[36:39], v[176:179], v[226:229], v[36:39]
	v_mfma_f32_16x16x32_bf16 v[28:31], v[168:171], v[234:237], v[28:31]
	v_mfma_f32_16x16x32_bf16 v[20:23], v[176:179], v[234:237], v[20:23]
	v_mfma_f32_16x16x32_bf16 v[12:15], v[168:171], v[242:245], v[12:15]
	v_mfma_f32_16x16x32_bf16 v[4:7], v[176:179], v[242:245], v[4:7]
	s_setprio 0
	s_setprio 1
	v_mfma_f32_16x16x32_bf16 v[56:59], v[180:183], v[214:217], v[56:59]
	v_mfma_f32_16x16x32_bf16 v[48:51], v[188:191], v[214:217], v[48:51]
	v_mfma_f32_16x16x32_bf16 v[40:43], v[180:183], v[222:225], v[40:43]
	v_mfma_f32_16x16x32_bf16 v[32:35], v[188:191], v[222:225], v[32:35]
	v_mfma_f32_16x16x32_bf16 v[24:27], v[180:183], v[230:233], v[24:27]
	v_mfma_f32_16x16x32_bf16 v[16:19], v[188:191], v[230:233], v[16:19]
	v_mfma_f32_16x16x32_bf16 v[8:11], v[180:183], v[238:241], v[8:11]
	v_mfma_f32_16x16x32_bf16 v[0:3], v[188:191], v[238:241], v[0:3]
	v_mfma_f32_16x16x32_bf16 v[56:59], v[184:187], v[218:221], v[56:59]
	v_mfma_f32_16x16x32_bf16 v[48:51], v[210:213], v[218:221], v[48:51]
	v_mfma_f32_16x16x32_bf16 v[40:43], v[184:187], v[226:229], v[40:43]
	v_mfma_f32_16x16x32_bf16 v[32:35], v[210:213], v[226:229], v[32:35]
	v_mfma_f32_16x16x32_bf16 v[24:27], v[184:187], v[234:237], v[24:27]
	v_mfma_f32_16x16x32_bf16 v[16:19], v[210:213], v[234:237], v[16:19]
	v_mfma_f32_16x16x32_bf16 v[8:11], v[184:187], v[242:245], v[8:11]
	v_mfma_f32_16x16x32_bf16 v[0:3], v[210:213], v[242:245], v[0:3]
	s_setprio 0
	s_barrier
	s_add_i32 s53, s53, 2
	s_add_u32 s14, s14, 0x100
	s_addc_u32 s15, s15, 0
	s_add_u32 s51, s51, 0x100
	s_addc_u32 s52, s52, 0
	s_cmp_gt_u32 s53, 13
	s_cbranch_scc0 .LBB0_446
	s_add_u32 s100, s49, 0x40080
	s_addc_u32 s101, s7, 0
	s_mov_b32 m0, s43
	v_lshl_add_u64 v[162:163], s[100:101], 0, v[136:137]
	global_load_lds_dwordx4 v[162:163], off
	v_lshl_add_u64 v[162:163], s[100:101], 0, v[138:139]
	s_mov_b32 m0, s44
	s_nop 0
	global_load_lds_dwordx4 v[162:163], off
	s_and_b64 vcc, exec, s[2:3]
	s_cbranch_vccz .LBB0_449
	s_barrier

; __global__ void __launch_bounds__(NTHR) mk_fwd(Args args) {
	.amdhsa_kernel _Z6mk_fwd4Args
		.amdhsa_group_segment_fixed_size 147456
		.amdhsa_private_segment_fixed_size 0
		.amdhsa_kernarg_size 480
		.amdhsa_user_sgpr_count 2
		.amdhsa_user_sgpr_dispatch_ptr 0
		.amdhsa_user_sgpr_queue_ptr 0
		.amdhsa_user_sgpr_kernarg_segment_ptr 1
		.amdhsa_user_sgpr_dispatch_id 0
		.amdhsa_user_sgpr_kernarg_preload_length 0
		.amdhsa_user_sgpr_kernarg_preload_offset 0
		.amdhsa_user_sgpr_private_segment_size 0
		.amdhsa_uses_dynamic_stack 0
		.amdhsa_enable_private_segment 0
		.amdhsa_system_sgpr_workgroup_id_x 1
		.amdhsa_system_sgpr_workgroup_id_y 0
		.amdhsa_system_sgpr_workgroup_id_z 0
		.amdhsa_system_sgpr_workgroup_info 0
		.amdhsa_system_vgpr_workitem_id 2
		.amdhsa_next_free_vgpr 256
		.amdhsa_next_free_sgpr 102
		.amdhsa_accum_offset 256
		.amdhsa_reserve_vcc 1
		.amdhsa_float_round_mode_32 0
		.amdhsa_float_round_mode_16_64 0
		.amdhsa_float_denorm_mode_32 3
		.amdhsa_float_denorm_mode_16_64 3
		.amdhsa_dx10_clamp 1
		.amdhsa_ieee_mode 1
		.amdhsa_fp16_overflow 0
		.amdhsa_tg_split 0
		.amdhsa_exception_fp_ieee_invalid_op 0
		.amdhsa_exception_fp_denorm_src 0
		.amdhsa_exception_fp_ieee_div_zero 0
		.amdhsa_exception_fp_ieee_overflow 0
		.amdhsa_exception_fp_ieee_underflow 0
		.amdhsa_exception_fp_ieee_inexact 0
		.amdhsa_exception_int_div_zero 0
	.end_amdhsa_kernel

; __global__ void __launch_bounds__(NTHR) mk_fwd(Args args) {
amdhsa.kernels:
  - .agpr_count:     0
    .args:
      - .offset:         0
        .size:           224
        .value_kind:     by_value
      - .offset:         224
        .size:           4
        .value_kind:     hidden_block_count_x
      - .offset:         228
        .size:           4
        .value_kind:     hidden_block_count_y
      - .offset:         232
        .size:           4
        .value_kind:     hidden_block_count_z
      - .offset:         236
        .size:           2
        .value_kind:     hidden_group_size_x
      - .offset:         238
        .size:           2
        .value_kind:     hidden_group_size_y
      - .offset:         240
        .size:           2
        .value_kind:     hidden_group_size_z
      - .offset:         242
        .size:           2
        .value_kind:     hidden_remainder_x
      - .offset:         244
        .size:           2
        .value_kind:     hidden_remainder_y
      - .offset:         246
        .size:           2
        .value_kind:     hidden_remainder_z
      - .offset:         264
        .size:           8
        .value_kind:     hidden_global_offset_x
      - .offset:         272
        .size:           8
        .value_kind:     hidden_global_offset_y
      - .offset:         280
        .size:           8
        .value_kind:     hidden_global_offset_z
      - .offset:         288
        .size:           2
        .value_kind:     hidden_grid_dims
      - .offset:         312
        .size:           8
        .value_kind:     hidden_multigrid_sync_arg
    .group_segment_fixed_size: 147456
    .kernarg_segment_align: 8
    .kernarg_segment_size: 480
    .language:       OpenCL C
    .language_version:
      - 2
      - 0
    .max_flat_workgroup_size: 512
    .name:           _Z6mk_fwd4Args
    .private_segment_fixed_size: 0
    .sgpr_count:     108
    .sgpr_spill_count: 193
    .symbol:         _Z6mk_fwd4Args.kd
    .uniform_work_group_size: 1
    .uses_dynamic_stack: false
    .vgpr_count:     256
    .vgpr_spill_count: 0
    .wavefront_size: 64
